# static s_setprio 1 for waves 0-3 (the other half) across the attention phase
# speedup vs baseline: 1.0020x; 1.0020x over previous
; #define LAS __attribute__((address_space(3)))
; #define PH_BEGIN(k) if (lo <= ph && ph < hi) { if constexpr ((EN >> (k)) & 1) for (int rep_ = 0; rep_ < ((((REP) >> (k)) & 1) ? 2 : 1); ++rep_) {
; __global__ void __launch_bounds__(512, 2) mega_fwd(Args a) {
;     ...
;         PH_BEGIN(3)
;         {
;             unsigned* qc = ctl + 512 + l;
;             volatile LAS int* qslot = (volatile LAS int*)(lds + LDS_BYTES - 32);
;             for (;;) {
;                 if (tid == 0) *qslot = (int)atomicAdd(qc, 1u);
;                 __syncthreads();
;                 const int it = __builtin_amdgcn_readfirstlane(*qslot);
;                 __syncthreads();
;                 if (it >= 768) break;
.Lcve_done:
	v_readfirstlane_b32 s100, v166
	s_nop 3
	s_lshr_b32 s100, s100, 6
	s_cmp_ge_u32 s100, 4
	s_cbranch_scc1 .Lattn_prio_skip
	s_setprio 1
